# attention g==2 iterations: lse/og loads no longer waited at issue; wait moved to the merge block as vmcnt(6), last iteration waits vmcnt(0)
# speedup vs baseline: 1.0016x; 1.0016x over previous
; #define LAS __attribute__((address_space(3)))
; #define SCHED_BAR() __builtin_amdgcn_sched_barrier(0)
; #define LDS_BARRIER() do { asm volatile("s_waitcnt lgkmcnt(0)" ::: "memory"); __builtin_amdgcn_s_barrier(); asm volatile("" ::: "memory"); } while (0)
; __device__ __forceinline__ void attn_unit(LAS unsigned char* lds, bf16_t* proj, bf16_t* og, float* lse, int unit) {
;     ...
;         if (it == 32) { asm volatile("s_waitcnt vmcnt(0)" ::: "memory"); __syncthreads(); }
;         LDS_BARRIER();
; #pragma unroll
;         for (int i = 0; i < 2; ++i) { const int p = tid + 512 * i, kc = p >> 3, pc = p & 7;
;             *(LAS u32x4*)(KI + (par * 128 + kc) * AT_P + pc * 16) = kreg[i]; *(LAS u32x4*)(VI + (par * 128 + kc) * AT_P + pc * 16) = vreg[i]; }
;         bf16x8 Qf[2]; Qf[0] = Qn[0]; Qf[1] = Qn[1];
;         const int tokq = (128 * blk + qi) * dil + r; const size_t rowq = (size_t)b * SEQ + tokq;
;         float l0 = 0.f, l1 = 0.f; u32x2 c0[4], c1[4];
; #pragma unroll
;         for (int et = 0; et < 4; ++et) { c0[et] = (u32x2){0u, 0u}; c1[et] = (u32x2){0u, 0u}; }
;         SCHED_BAR();
;         if (g == 2) {
;             l0 = lse[((size_t)0 * 128 + unit) * SEQ + tokq]; l1 = lse[((size_t)1 * 128 + unit) * SEQ + tokq];
;             const bf16_t* o0p = og + ((size_t)0 * MP + rowq) * 512 + h * 64 + 4 * fq; const bf16_t* o1p = og + ((size_t)1 * MP + rowq) * 512 + h * 64 + 4 * fq;
; #pragma unroll
;             for (int et = 0; et < 4; ++et) { c0[et] = *(const u32x2*)(o0p + 16 * et); c1[et] = *(const u32x2*)(o1p + 16 * et); }
;         }
.LBB0_1317:
	s_and_b32 s92, s89, 0x80
	v_or_b32_e32 v16, s92, v158
	v_mad_u32_u24 v16, v16, s78, v41
	s_waitcnt lgkmcnt(0)
	s_barrier
	s_nop 0
	ds_write_b128 v16, v[0:3]
	s_nop 0
	ds_write_b128 v16, v[8:11] offset:39168
	v_add_u32_e32 v16, s92, v40
	v_mad_u32_u24 v16, v16, s78, v41
	s_lshl_b32 s95, s91, 7
	s_lshl_b32 s94, s90, 1
	ds_write_b128 v16, v[4:7]
	s_nop 0
	ds_write_b128 v16, v[12:15] offset:39168
	v_add_u32_e32 v16, s95, v54
	v_lshlrev_b32_e32 v16, s94, v16
	v_add_u32_e32 v60, s2, v16
	v_ashrrev_i32_e32 v61, 31, v60
	v_lshl_add_u64 v[62:63], s[26:27], 0, v[60:61]
	s_andn2_b64 vcc, exec, s[76:77]
	s_cbranch_vccnz .LBB0_1319
	v_readlane_b32 s76, v249, 41
	v_lshlrev_b64 v[16:17], 2, v[60:61]
	v_readlane_b32 s77, v249, 42
	v_lshl_add_u64 v[18:19], s[28:29], 0, v[16:17]
	v_lshlrev_b64 v[20:21], 10, v[62:63]
	v_lshl_add_u64 v[16:17], s[76:77], 0, v[16:17]
	v_readlane_b32 s76, v254, 49
	v_readlane_b32 s77, v254, 50
	s_lshl_b32 s2, s7, 1
	v_lshlrev_b32_e32 v22, 1, v162
	v_lshl_add_u64 v[20:21], s[76:77], 0, v[20:21]
	v_lshl_add_u64 v[20:21], v[20:21], 0, s[2:3]
	v_mov_b32_e32 v23, v161
	v_lshl_add_u64 v[20:21], v[20:21], 0, v[22:23]
	s_mov_b32 s2, 0x2040000
	s_mov_b64 s[76:77], 0x2040000
	v_add_co_u32_e32 v32, vcc, s2, v20
	v_lshl_add_u64 v[22:23], v[20:21], 0, s[76:77]
	s_nop 0
	v_addc_co_u32_e32 v33, vcc, 0, v21, vcc
	global_load_dword v108, v[18:19], off
	global_load_dword v55, v[16:17], off
	global_load_dwordx2 v[76:77], v[20:21], off
	global_load_dwordx2 v[72:73], v[20:21], off offset:32
	global_load_dwordx2 v[74:75], v[22:23], off offset:32
	global_load_dwordx2 v[68:69], v[20:21], off offset:64
	global_load_dwordx2 v[70:71], v[22:23], off offset:64
	global_load_dwordx2 v[64:65], v[20:21], off offset:96
	global_load_dwordx2 v[78:79], v[32:33], off
	global_load_dwordx2 v[66:67], v[22:23], off offset:96
	s_branch .LBB0_1320

; #define SCHED_BAR() __builtin_amdgcn_sched_barrier(0)
; #define LDS_BARRIER() do { asm volatile("s_waitcnt lgkmcnt(0)" ::: "memory"); __builtin_amdgcn_s_barrier(); asm volatile("" ::: "memory"); } while (0)
; __device__ __forceinline__ void attn_unit(LAS unsigned char* lds, bf16_t* proj, bf16_t* og, float* lse, int unit) {
;     ...
;         if (it + 1 < 48) ATT_LOAD(it + 1);
;         SCHED_BAR();
;         LDS_BARRIER();
.Latt_lastit:
	s_waitcnt vmcnt(0)
	s_branch .LBB0_1329

; #define LAS __attribute__((address_space(3)))
; #define SCHED_BAR() __builtin_amdgcn_sched_barrier(0)
; #define LDS_BARRIER() do { asm volatile("s_waitcnt lgkmcnt(0)" ::: "memory"); __builtin_amdgcn_s_barrier(); asm volatile("" ::: "memory"); } while (0)
; __device__ __forceinline__ void attn_unit(LAS unsigned char* lds, bf16_t* proj, bf16_t* og, float* lse, int unit) {
;     ...
;         LDS_BARRIER();
;     ...
;         f32x4 S[10]; float mx = -1e30f;
; #pragma unroll
;         for (int hb = 0; hb < 2; ++hb) { bf16x8 F[10];
; #pragma unroll
;             for (int k5 = 0; k5 < 5; ++k5) { const int tr0 = ATT_TROW(w + 5 * hb + k5);
; #pragma unroll
;                 for (int ks = 0; ks < 2; ++ks) F[2 * k5 + ks] = *(const LAS bf16x8*)(KI + (tr0 + l16) * AT_P + (32 * ks + 8 * fq) * 2); }
;             SCHED_BAR();
; #pragma unroll
;             for (int k5 = 0; k5 < 5; ++k5) S[5 * hb + k5] = __builtin_amdgcn_mfma_f32_16x16x32_bf16(F[2 * k5], Qf[0], (f32x4){0.f, 0.f, 0.f, 0.f}, 0, 0, 0);
; #pragma unroll
;             for (int k5 = 0; k5 < 5; ++k5) S[5 * hb + k5] = __builtin_amdgcn_mfma_f32_16x16x32_bf16(F[2 * k5 + 1], Qf[1], S[5 * hb + k5], 0, 0, 0);
;             SCHED_BAR(); }
.LBB0_1329:
	s_xor_b64 s[76:77], s[0:1], -1
	s_or_b32 s0, s92, s79
	s_add_i32 vcc_lo, s92, 0xffffff80
	s_xor_b32 s2, s0, 0x80
	v_readlane_b32 s0, v249, 1
	s_add_i32 s93, vcc_lo, s79
	v_readlane_b32 s1, v249, 2
	s_and_b64 s[0:1], s[0:1], exec
	s_cselect_b32 s93, s93, 0x100
	s_and_b64 s[0:1], s[34:35], exec
	s_cselect_b32 s94, s2, s93
	v_or_b32_e32 v32, s94, v156
	v_mad_u64_u32 v[36:37], s[0:1], v32, s78, v[42:43]
	s_or_b32 s0, s92, s80
	s_xor_b32 s2, s0, 0x80
	s_add_i32 s93, vcc_lo, s80
	s_and_b64 s[0:1], s[40:41], exec
	s_cselect_b32 s93, s93, 0x100
	s_and_b64 s[0:1], s[38:39], exec
	s_cselect_b32 s0, s2, s93
	v_or_b32_e32 v109, s0, v156
	v_mad_u64_u32 v[114:115], s[0:1], v109, s78, v[42:43]
	s_or_b32 s0, s92, s81
	s_xor_b32 s2, s0, 0x80
	v_readlane_b32 s0, v249, 29
	s_add_i32 s93, vcc_lo, s81
	v_readlane_b32 s1, v249, 30
	s_and_b64 s[0:1], s[0:1], exec
	v_readlane_b32 s0, v249, 27
	v_readlane_b32 s1, v249, 28
	s_cselect_b32 s93, s93, 0x100
	s_and_b64 s[0:1], s[0:1], exec
	s_cselect_b32 s93, s2, s93
	v_or_b32_e32 v109, s93, v156
	v_mad_u64_u32 v[122:123], s[0:1], v109, s78, v[42:43]
	s_or_b32 s0, s92, s82
	s_xor_b32 s2, s0, 0x80
	s_add_i32 s96, vcc_lo, s82
	s_and_b64 s[0:1], s[48:49], exec
	s_cselect_b32 s96, s96, 0x100
	s_and_b64 s[0:1], s[46:47], exec
	s_cselect_b32 s0, s2, s96
	v_or_b32_e32 v109, s0, v156
	v_mad_u64_u32 v[130:131], s[0:1], v109, s78, v[42:43]
	s_or_b32 s0, s92, s83
	s_xor_b32 s2, s0, 0x80
	v_readlane_b32 s0, v249, 33
	s_add_i32 s96, vcc_lo, s83
	v_readlane_b32 s1, v249, 34
	s_and_b64 s[0:1], s[0:1], exec
	v_readlane_b32 s0, v249, 31
	v_readlane_b32 s1, v249, 32
	s_cselect_b32 s96, s96, 0x100
	s_and_b64 s[0:1], s[0:1], exec
	s_cselect_b32 s2, s2, s96
	v_or_b32_e32 v109, s2, v156
	s_waitcnt lgkmcnt(0)
	s_barrier
	v_mad_u64_u32 v[138:139], s[0:1], v109, s78, v[42:43]
	ds_read_b128 v[32:35], v36
	ds_read_b128 v[36:39], v36 offset:64
	ds_read_b128 v[110:113], v114
	ds_read_b128 v[114:117], v114 offset:64
	ds_read_b128 v[118:121], v122
	ds_read_b128 v[122:125], v122 offset:64
	ds_read_b128 v[126:129], v130
	ds_read_b128 v[130:133], v130 offset:64
	ds_read_b128 v[134:137], v138
	ds_read_b128 v[138:141], v138 offset:64
	s_waitcnt lgkmcnt(9)
	v_mfma_f32_16x16x32_bf16 v[32:35], v[32:35], v[28:31], 0
	s_waitcnt lgkmcnt(7)
	v_mfma_f32_16x16x32_bf16 v[110:113], v[110:113], v[28:31], 0
	s_waitcnt lgkmcnt(5)
	v_mfma_f32_16x16x32_bf16 v[118:121], v[118:121], v[28:31], 0
	s_waitcnt lgkmcnt(3)
	v_mfma_f32_16x16x32_bf16 v[126:129], v[126:129], v[28:31], 0
	s_waitcnt lgkmcnt(1)
	v_mfma_f32_16x16x32_bf16 v[134:137], v[134:137], v[28:31], 0
	v_mfma_f32_16x16x32_bf16 v[32:35], v[36:39], v[24:27], v[32:35]
	v_mfma_f32_16x16x32_bf16 v[36:39], v[114:117], v[24:27], v[110:113]
	v_mfma_f32_16x16x32_bf16 v[110:113], v[122:125], v[24:27], v[118:121]
	v_mfma_f32_16x16x32_bf16 v[114:117], v[130:133], v[24:27], v[126:129]
	s_waitcnt lgkmcnt(0)
	v_mfma_f32_16x16x32_bf16 v[118:121], v[138:141], v[24:27], v[134:137]
	s_or_b32 s0, s92, s84
	s_xor_b32 s96, s0, 0x80
	s_add_i32 s97, vcc_lo, s84
	s_and_b64 s[0:1], s[56:57], exec
	s_cselect_b32 s97, s97, 0x100
	s_and_b64 s[0:1], s[54:55], exec
	s_cselect_b32 s0, s96, s97
	v_or_b32_e32 v109, s0, v156
	v_mad_u64_u32 v[126:127], s[0:1], v109, s78, v[42:43]
	s_or_b32 s0, s92, s85
	s_xor_b32 s96, s0, 0x80
	v_readlane_b32 s0, v249, 21
	s_add_i32 s97, vcc_lo, s85
	v_readlane_b32 s1, v249, 22
	s_and_b64 s[0:1], s[0:1], exec
	v_readlane_b32 s0, v249, 19
	v_readlane_b32 s1, v249, 20
	s_cselect_b32 s97, s97, 0x100
	s_and_b64 s[0:1], s[0:1], exec
	s_cselect_b32 s1, s96, s97
	s_xor_b32 s0, s92, 0xf0
	s_add_i32 vcc_hi, vcc_lo, s86
	s_and_b64 s[96:97], s[64:65], exec
	s_cselect_b32 vcc_hi, vcc_hi, 0x100
	s_and_b64 s[96:97], s[62:63], exec
	v_or_b32_e32 v109, s1, v156
	s_cselect_b32 s0, s0, vcc_hi
	v_mad_u64_u32 v[134:135], s[96:97], v109, s78, v[42:43]
	v_or_b32_e32 v109, s0, v156
	s_add_i32 s0, s92, s79
	s_and_b64 s[96:97], s[34:35], exec
	s_cselect_b32 s0, s0, 0x100
	v_mad_u64_u32 v[142:143], s[96:97], v109, s78, v[42:43]
	v_or_b32_e32 v109, s0, v156
	s_add_i32 vcc_lo, vcc_lo, s88
	v_mad_u64_u32 v[150:151], s[96:97], v109, s78, v[42:43]
	s_and_b64 s[96:97], s[38:39], exec
	s_cselect_b32 s96, vcc_lo, 0x100
	v_or_b32_e32 v109, s96, v156
	v_mad_u64_u32 v[154:155], s[96:97], v109, s78, v[42:43]
	ds_read_b128 v[122:125], v126
	ds_read_b128 v[126:129], v126 offset:64
	ds_read_b128 v[130:133], v134
	ds_read_b128 v[134:137], v134 offset:64
	ds_read_b128 v[138:141], v142
	ds_read_b128 v[142:145], v142 offset:64
	ds_read_b128 v[146:149], v150
	ds_read_b128 v[150:153], v150 offset:64
	ds_read_b128 v[164:167], v154
	ds_read_b128 v[168:171], v154 offset:64
	s_waitcnt lgkmcnt(9)
	v_mfma_f32_16x16x32_bf16 v[122:125], v[122:125], v[28:31], 0
	s_waitcnt lgkmcnt(7)
	v_mfma_f32_16x16x32_bf16 v[130:133], v[130:133], v[28:31], 0
	s_waitcnt lgkmcnt(5)
	v_mfma_f32_16x16x32_bf16 v[138:141], v[138:141], v[28:31], 0
	s_waitcnt lgkmcnt(3)
	v_mfma_f32_16x16x32_bf16 v[146:149], v[146:149], v[28:31], 0
	s_waitcnt lgkmcnt(1)
	v_mfma_f32_16x16x32_bf16 v[28:31], v[164:167], v[28:31], 0
	v_mfma_f32_16x16x32_bf16 v[122:125], v[126:129], v[24:27], v[122:125]
	v_mfma_f32_16x16x32_bf16 v[126:129], v[134:137], v[24:27], v[130:133]
	v_mfma_f32_16x16x32_bf16 v[130:133], v[142:145], v[24:27], v[138:141]
	v_mfma_f32_16x16x32_bf16 v[134:137], v[150:153], v[24:27], v[146:149]
	s_waitcnt lgkmcnt(0)
; __device__ __forceinline__ void attn_unit(LAS unsigned char* lds, bf16_t* proj, bf16_t* og, float* lse, int unit) {
;     ...
; #pragma unroll
;         for (int kt = 0; kt < 10; ++kt)
; #pragma unroll
;             for (int jj = 0; jj < 4; ++jj) { const int kc = 16 * (w + kt) + 4 * fq + jj;
;                 const bool valid = (kc >= qi) && (kc <= qi + 128) && (128 * (blk - 1) + kc >= 0);
;                 const float sv = valid ? S[kt][jj] : -1e30f; S[kt][jj] = sv; mx = fmaxf(mx, sv); }
;         mx = fmaxf(mx, __shfl_xor(mx, 16)); mx = fmaxf(mx, __shfl_xor(mx, 32));
	v_mfma_f32_16x16x32_bf16 v[24:27], v[168:171], v[24:27], v[28:31]
	s_sub_i32 s95, 0x7f, s95
	v_cmp_lt_i32_e32 vcc, s95, v84
	s_and_b64 vcc, s[74:75], vcc
	v_readlane_b32 s96, v249, 7
	v_cndmask_b32_e32 v28, v81, v32, vcc
	v_cmp_le_i32_e32 vcc, s95, v84
	v_readlane_b32 s97, v249, 8
	s_and_b64 vcc, s[96:97], vcc
	v_cndmask_b32_e32 v29, v81, v33, vcc
	s_mov_b32 s96, 0xf149f2ca
	v_max3_f32 v30, v28, s96, v29
	v_readlane_b32 s96, v249, 9
	v_cmp_lt_i32_e32 vcc, s95, v85
	v_readlane_b32 s97, v249, 10
	s_and_b64 vcc, s[96:97], vcc
	v_readlane_b32 s96, v249, 11
	v_cndmask_b32_e32 v31, v81, v34, vcc
	v_cmp_lt_i32_e32 vcc, s95, v86
	v_readlane_b32 s97, v249, 12
	s_and_b64 vcc, s[96:97], vcc
	v_readlane_b32 s96, v249, 13
	v_cndmask_b32_e32 v32, v81, v35, vcc
	v_cmp_lt_i32_e32 vcc, s95, v87
	v_readlane_b32 s97, v249, 14
	s_and_b64 vcc, s[96:97], vcc
	v_readlane_b32 s96, v249, 15
	v_cndmask_b32_e32 v33, v81, v36, vcc
	v_cmp_le_i32_e32 vcc, s95, v87
	v_readlane_b32 s97, v249, 16
	s_and_b64 vcc, s[96:97], vcc
	v_readlane_b32 s96, v249, 17
	v_cndmask_b32_e32 v34, v81, v37, vcc
	v_cmp_lt_i32_e32 vcc, s95, v88
	v_readlane_b32 s97, v249, 18
	s_and_b64 vcc, s[96:97], vcc
	v_readlane_b32 s96, v249, 23
	v_cndmask_b32_e32 v35, v81, v38, vcc
	v_cmp_lt_i32_e32 vcc, s95, v89
	v_readlane_b32 s97, v249, 24
	s_and_b64 vcc, s[96:97], vcc
	v_readlane_b32 s96, v249, 25
	v_cndmask_b32_e32 v36, v81, v39, vcc
	v_cmp_lt_i32_e32 vcc, s95, v90
	v_readlane_b32 s97, v249, 26
	s_and_b64 vcc, s[96:97], vcc
	v_readlane_b32 s96, v249, 3
	v_cndmask_b32_e32 v37, v81, v110, vcc
	v_cmp_le_i32_e32 vcc, s95, v90
	v_readlane_b32 s97, v249, 4
	s_and_b64 vcc, s[96:97], vcc
	v_readlane_b32 s96, v249, 5
	v_cndmask_b32_e32 v38, v81, v111, vcc
	v_cmp_lt_i32_e32 vcc, s95, v91
	v_readlane_b32 s97, v249, 6
	s_and_b64 vcc, s[96:97], vcc
	v_readlane_b32 s96, v249, 43
	v_cndmask_b32_e32 v39, v81, v112, vcc
	v_cmp_lt_i32_e32 vcc, s95, v92
	v_readlane_b32 s97, v249, 44
	s_and_b64 vcc, s[96:97], vcc
	v_readlane_b32 s96, v249, 45
	v_cndmask_b32_e32 v110, v81, v113, vcc
	v_cmp_lt_i32_e32 vcc, s95, v93
	v_readlane_b32 s97, v249, 46
	s_and_b64 vcc, s[96:97], vcc
	v_readlane_b32 s96, v249, 47
	v_cndmask_b32_e32 v111, v81, v114, vcc
	v_cmp_le_i32_e32 vcc, s95, v93
	v_readlane_b32 s97, v249, 48
	s_and_b64 vcc, s[96:97], vcc
	v_readlane_b32 s96, v249, 49
	v_cndmask_b32_e32 v112, v81, v115, vcc
	v_cmp_lt_i32_e32 vcc, s95, v94
	v_readlane_b32 s97, v249, 50
	s_and_b64 vcc, s[96:97], vcc
	v_readlane_b32 s96, v249, 51
	v_cndmask_b32_e32 v113, v81, v116, vcc
	v_cmp_lt_i32_e32 vcc, s95, v95
	v_readlane_b32 s97, v249, 52
	s_and_b64 vcc, s[96:97], vcc
	v_readlane_b32 s96, v249, 53
	v_cndmask_b32_e32 v114, v81, v117, vcc
	v_cmp_lt_i32_e32 vcc, s95, v96
	v_readlane_b32 s97, v249, 54
	s_and_b64 vcc, s[96:97], vcc
	v_readlane_b32 s96, v249, 55
	v_cndmask_b32_e32 v115, v81, v118, vcc
	v_cmp_le_i32_e32 vcc, s95, v96
	v_readlane_b32 s97, v249, 56
	s_and_b64 vcc, s[96:97], vcc
	v_cndmask_b32_e32 v116, v81, v119, vcc
	v_cmp_lt_i32_e32 vcc, s95, v97
	s_and_b64 vcc, s[24:25], vcc
	v_max3_f32 v30, v30, v31, v32
	v_cndmask_b32_e32 v117, v81, v120, vcc
	v_cmp_lt_i32_e32 vcc, s95, v98
	s_and_b64 vcc, s[4:5], vcc
	v_max3_f32 v30, v30, v33, v34
	v_cndmask_b32_e32 v119, v81, v121, vcc
	v_cmp_lt_i32_e32 vcc, s95, v99
	s_and_b64 vcc, s[30:31], vcc
	v_max3_f32 v30, v30, v35, v36
	v_cndmask_b32_e32 v120, v81, v122, vcc
	v_cmp_le_i32_e32 vcc, s95, v99
	s_and_b64 vcc, s[36:37], vcc
	v_max3_f32 v30, v30, v37, v38
	v_cndmask_b32_e32 v121, v81, v123, vcc
	v_cmp_lt_i32_e32 vcc, s95, v100
	s_and_b64 vcc, s[42:43], vcc
	v_max3_f32 v30, v30, v39, v110
	v_cndmask_b32_e32 v123, v81, v124, vcc
	v_cmp_lt_i32_e32 vcc, s95, v101
	s_and_b64 vcc, s[44:45], vcc
	v_max3_f32 v30, v30, v111, v112
	v_cndmask_b32_e32 v125, v81, v125, vcc
	v_cmp_lt_i32_e32 vcc, s95, v102
	s_and_b64 vcc, s[50:51], vcc
	v_max3_f32 v30, v30, v113, v114
	v_cndmask_b32_e32 v138, v81, v126, vcc
	v_cmp_le_i32_e32 vcc, s95, v102
	s_and_b64 vcc, s[52:53], vcc
	v_max3_f32 v30, v30, v115, v116
	v_cndmask_b32_e32 v139, v81, v127, vcc
	v_cmp_lt_i32_e32 vcc, s95, v103
	s_and_b64 vcc, s[58:59], vcc
	v_max3_f32 v30, v30, v117, v119
	v_cndmask_b32_e32 v140, v81, v128, vcc
	v_cmp_lt_i32_e32 vcc, s95, v104
	s_and_b64 vcc, s[60:61], vcc
	v_max3_f32 v30, v30, v120, v121
	v_cndmask_b32_e32 v141, v81, v129, vcc
	v_cmp_lt_i32_e32 vcc, s95, v105
	s_and_b64 vcc, s[66:67], vcc
	v_max3_f32 v30, v30, v123, v125
	v_cndmask_b32_e32 v142, v81, v130, vcc
	v_cmp_le_i32_e32 vcc, s95, v105
	s_and_b64 vcc, s[68:69], vcc
	v_max3_f32 v30, v30, v138, v139
	v_cndmask_b32_e32 v143, v81, v131, vcc
	v_cmp_lt_i32_e32 vcc, s95, v106
	s_and_b64 vcc, s[70:71], vcc
	v_max3_f32 v30, v30, v140, v141
	v_cndmask_b32_e32 v132, v81, v132, vcc
	v_cmp_lt_i32_e32 vcc, s95, v107
	s_and_b64 vcc, s[72:73], vcc
	v_max3_f32 v30, v30, v142, v143
	v_cndmask_b32_e32 v133, v81, v133, vcc
	v_max3_f32 v30, v30, v132, v133
	v_cndmask_b32_e64 v134, v81, v134, s[8:9]
	v_cndmask_b32_e64 v135, v81, v135, s[10:11]
	v_and_b32_e32 v118, 64, v82
	v_max3_f32 v30, v30, v134, v135
	v_cndmask_b32_e64 v136, v81, v136, s[12:13]
	v_cndmask_b32_e64 v137, v81, v137, s[14:15]
	v_xor_b32_e32 v109, 16, v82
	v_add_u32_e32 v118, 64, v118
	v_max3_f32 v30, v30, v136, v137
	v_cndmask_b32_e64 v24, v81, v24, s[16:17]
	v_cndmask_b32_e64 v25, v81, v25, s[18:19]
	v_cmp_lt_i32_e32 vcc, v109, v118
	v_max3_f32 v30, v30, v24, v25
	v_cndmask_b32_e64 v26, v81, v26, s[20:21]
	v_cndmask_b32_e64 v27, v81, v27, s[22:23]
	v_cndmask_b32_e32 v109, v82, v109, vcc
	v_max3_f32 v30, v30, v26, v27
	v_lshlrev_b32_e32 v144, 2, v109
	ds_bpermute_b32 v109, v144, v30
	s_add_i32 s95, s92, 0xffffff90
	s_xor_b32 s92, s92, 0x90
	s_waitcnt lgkmcnt(0)
; __device__ __forceinline__ void attn_unit(LAS unsigned char* lds, bf16_t* proj, bf16_t* og, float* lse, int unit) {
;     ...
;         mx = fmaxf(mx, __shfl_xor(mx, 16)); mx = fmaxf(mx, __shfl_xor(mx, 32));
;         float l = 0.f;
; #pragma unroll
;         for (int kt = 0; kt < 10; ++kt)
; #pragma unroll
;             for (int jj = 0; jj < 4; ++jj) { const float pv = __expf(S[kt][jj] - mx); S[kt][jj] = pv; l += pv; }
;         l += __shfl_xor(l, 16); l += __shfl_xor(l, 32);
	v_max_f32_e32 v109, v109, v109
	v_max_f32_e32 v30, v30, v109
	v_xor_b32_e32 v109, 32, v82
	v_cmp_lt_i32_e32 vcc, v109, v118
	s_nop 1
	v_cndmask_b32_e32 v109, v82, v109, vcc
	v_lshlrev_b32_e32 v145, 2, v109
	ds_bpermute_b32 v109, v145, v30
	s_add_i32 vcc_lo, s92, s79
	s_add_i32 vcc_hi, s95, s79
	s_and_b64 s[96:97], s[40:41], exec
	s_cselect_b32 vcc_hi, vcc_hi, 0x100
	s_waitcnt lgkmcnt(0)
	v_max_f32_e32 v109, v109, v109
	v_max_f32_e32 v109, v30, v109
	v_sub_f32_e32 v28, v28, v109
	v_mul_f32_e32 v28, 0x3fb8aa3b, v28
	v_exp_f32_e32 v146, v28
	v_sub_f32_e32 v28, v29, v109
	v_sub_f32_e32 v29, v33, v109
	v_mul_f32_e32 v29, 0x3fb8aa3b, v29
	v_exp_f32_e32 v150, v29
	v_sub_f32_e32 v29, v34, v109
	v_mul_f32_e32 v29, 0x3fb8aa3b, v29
	v_exp_f32_e32 v151, v29
	v_sub_f32_e32 v29, v35, v109
	v_mul_f32_e32 v29, 0x3fb8aa3b, v29
	v_exp_f32_e32 v152, v29
	v_sub_f32_e32 v29, v36, v109
	v_mul_f32_e32 v29, 0x3fb8aa3b, v29
	v_exp_f32_e32 v153, v29
	v_sub_f32_e32 v29, v37, v109
	v_mul_f32_e32 v29, 0x3fb8aa3b, v29
	v_exp_f32_e32 v122, v29
	v_sub_f32_e32 v29, v38, v109
	v_mul_f32_e32 v29, 0x3fb8aa3b, v29
	v_exp_f32_e32 v124, v29
	v_sub_f32_e32 v29, v39, v109
	v_mul_f32_e32 v29, 0x3fb8aa3b, v29
	v_exp_f32_e32 v126, v29
	v_sub_f32_e32 v29, v110, v109
	v_mul_f32_e32 v29, 0x3fb8aa3b, v29
	v_exp_f32_e32 v127, v29
	v_sub_f32_e32 v29, v111, v109
	v_mul_f32_e32 v29, 0x3fb8aa3b, v29
	v_exp_f32_e32 v128, v29
	v_sub_f32_e32 v29, v112, v109
	v_mul_f32_e32 v29, 0x3fb8aa3b, v29
	v_exp_f32_e32 v129, v29
	v_sub_f32_e32 v29, v113, v109
	v_mul_f32_e32 v29, 0x3fb8aa3b, v29
	v_exp_f32_e32 v130, v29
	v_sub_f32_e32 v29, v114, v109
	v_mul_f32_e32 v28, 0x3fb8aa3b, v28
	v_mul_f32_e32 v29, 0x3fb8aa3b, v29
	v_exp_f32_e32 v147, v28
	v_sub_f32_e32 v28, v31, v109
	v_exp_f32_e32 v131, v29
	v_sub_f32_e32 v29, v115, v109
	v_mul_f32_e32 v28, 0x3fb8aa3b, v28
	v_mul_f32_e32 v29, 0x3fb8aa3b, v29
	v_exp_f32_e32 v148, v28
	v_sub_f32_e32 v28, v32, v109
	v_exp_f32_e32 v114, v29
	v_sub_f32_e32 v29, v116, v109
	v_mul_f32_e32 v28, 0x3fb8aa3b, v28
	v_mul_f32_e32 v29, 0x3fb8aa3b, v29
	v_exp_f32_e32 v149, v28
	v_exp_f32_e32 v116, v29
	v_sub_f32_e32 v29, v117, v109
	v_add_f32_e32 v28, 0, v146
	v_mul_f32_e32 v29, 0x3fb8aa3b, v29
	v_add_f32_e32 v28, v147, v28
	v_exp_f32_e32 v118, v29
	v_sub_f32_e32 v29, v119, v109
	v_add_f32_e32 v28, v148, v28
	v_mul_f32_e32 v29, 0x3fb8aa3b, v29
	v_add_f32_e32 v28, v149, v28
	v_exp_f32_e32 v119, v29
	v_sub_f32_e32 v29, v120, v109
	v_add_f32_e32 v28, v150, v28
	v_mul_f32_e32 v29, 0x3fb8aa3b, v29
	v_add_f32_e32 v28, v151, v28
	v_exp_f32_e32 v120, v29
	v_sub_f32_e32 v29, v121, v109
	v_add_f32_e32 v28, v152, v28
	v_mul_f32_e32 v29, 0x3fb8aa3b, v29
	v_add_f32_e32 v28, v153, v28
	v_exp_f32_e32 v121, v29
	v_sub_f32_e32 v29, v123, v109
	v_add_f32_e32 v28, v122, v28
	v_mul_f32_e32 v29, 0x3fb8aa3b, v29
	v_add_f32_e32 v28, v124, v28
	v_exp_f32_e32 v123, v29
	v_sub_f32_e32 v29, v125, v109
	v_add_f32_e32 v28, v126, v28
	v_mul_f32_e32 v29, 0x3fb8aa3b, v29
	v_add_f32_e32 v28, v127, v28
	v_exp_f32_e32 v125, v29
	v_sub_f32_e32 v29, v138, v109
	v_add_f32_e32 v28, v128, v28
	v_mul_f32_e32 v29, 0x3fb8aa3b, v29
	v_add_f32_e32 v28, v129, v28
	v_exp_f32_e32 v34, v29
	v_sub_f32_e32 v29, v139, v109
	v_add_f32_e32 v28, v130, v28
	v_mul_f32_e32 v29, 0x3fb8aa3b, v29
	v_add_f32_e32 v28, v131, v28
	v_exp_f32_e32 v36, v29
	v_sub_f32_e32 v29, v140, v109
	v_add_f32_e32 v28, v114, v28
	v_mul_f32_e32 v29, 0x3fb8aa3b, v29
	v_add_f32_e32 v28, v116, v28
	v_exp_f32_e32 v38, v29
	v_sub_f32_e32 v29, v141, v109
	v_add_f32_e32 v28, v118, v28
	v_mul_f32_e32 v29, 0x3fb8aa3b, v29
	v_add_f32_e32 v28, v119, v28
	v_exp_f32_e32 v39, v29
	v_sub_f32_e32 v29, v142, v109
	v_add_f32_e32 v28, v120, v28
	v_mul_f32_e32 v29, 0x3fb8aa3b, v29
	v_add_f32_e32 v28, v121, v28
	v_exp_f32_e32 v112, v29
	v_sub_f32_e32 v29, v143, v109
	v_add_f32_e32 v28, v123, v28
	v_mul_f32_e32 v29, 0x3fb8aa3b, v29
	v_add_f32_e32 v28, v125, v28
	v_exp_f32_e32 v113, v29
	v_sub_f32_e32 v29, v132, v109
	v_add_f32_e32 v28, v34, v28
	v_mul_f32_e32 v29, 0x3fb8aa3b, v29
	v_add_f32_e32 v28, v36, v28
	v_exp_f32_e32 v115, v29
	v_sub_f32_e32 v29, v133, v109
	v_add_f32_e32 v28, v38, v28
	v_mul_f32_e32 v29, 0x3fb8aa3b, v29
	v_add_f32_e32 v28, v39, v28
	v_exp_f32_e32 v117, v29
	v_add_f32_e32 v28, v112, v28
	v_add_f32_e32 v28, v113, v28
	v_add_f32_e32 v28, v115, v28
	v_add_f32_e32 v32, v117, v28
	v_sub_f32_e32 v28, v134, v109
	v_mul_f32_e32 v28, 0x3fb8aa3b, v28
	v_sub_f32_e32 v29, v135, v109
	v_exp_f32_e32 v28, v28
	v_mul_f32_e32 v29, 0x3fb8aa3b, v29
	v_sub_f32_e32 v30, v136, v109
	v_exp_f32_e32 v29, v29
	v_mul_f32_e32 v30, 0x3fb8aa3b, v30
	v_sub_f32_e32 v31, v137, v109
	v_exp_f32_e32 v30, v30
	v_mul_f32_e32 v31, 0x3fb8aa3b, v31
	v_exp_f32_e32 v31, v31
	v_add_f32_e32 v32, v28, v32
	v_add_f32_e32 v32, v29, v32
	v_sub_f32_e32 v24, v24, v109
	v_add_f32_e32 v32, v30, v32
	v_mul_f32_e32 v24, 0x3fb8aa3b, v24
	v_add_f32_e32 v110, v31, v32
	v_exp_f32_e32 v32, v24
	v_sub_f32_e32 v24, v25, v109
	v_mul_f32_e32 v24, 0x3fb8aa3b, v24
	v_exp_f32_e32 v33, v24
	v_sub_f32_e32 v24, v26, v109
	v_mul_f32_e32 v24, 0x3fb8aa3b, v24
	v_exp_f32_e32 v35, v24
	v_sub_f32_e32 v24, v27, v109
	v_mul_f32_e32 v24, 0x3fb8aa3b, v24
	v_exp_f32_e32 v37, v24
	v_add_f32_e32 v24, v32, v110
	v_add_f32_e32 v24, v33, v24
	v_add_f32_e32 v24, v35, v24
	v_add_f32_e32 v24, v37, v24
	ds_bpermute_b32 v25, v144, v24
	s_and_b64 s[96:97], s[38:39], exec
	s_cselect_b32 s96, vcc_lo, vcc_hi
	v_or_b32_e32 v132, s94, v43
	v_or_b32_e32 v133, s96, v43
	s_waitcnt lgkmcnt(0)
; __device__ __forceinline__ bf16x8 cat8(s16x4 a, s16x4 b) { return __builtin_shufflevector(a, b, 0, 1, 2, 3, 4, 5, 6, 7); }
; __device__ __forceinline__ s16x4 trr(LAS unsigned char* p) { return __builtin_amdgcn_ds_read_tr16_b64_v4i16((LAS s16x4*)p); }
; #define SCHED_BAR() __builtin_amdgcn_sched_barrier(0)
; __device__ __forceinline__ void attn_unit(LAS unsigned char* lds, bf16_t* proj, bf16_t* og, float* lse, int unit) {
;     ...
;         f32x4 O[4];
; #pragma unroll
;         for (int et = 0; et < 4; ++et) O[et] = (f32x4){0.f, 0.f, 0.f, 0.f};
; #pragma unroll
;         for (int s5 = 0; s5 < 5; ++s5) { const bf16x8 Pf = pack8(S[2 * s5], S[2 * s5 + 1]); s16x4 tv[8];
;             const int ra = ATT_TROW(w + 2 * s5), rb2 = ATT_TROW(w + 2 * s5 + 1);
; #pragma unroll
;             for (int et = 0; et < 4; ++et) { tv[2 * et] = trr(VI + (ra + 4 * fq + tq) * AT_P + (16 * et + 4 * tp) * 2);
;                 tv[2 * et + 1] = trr(VI + (rb2 + 4 * fq + tq) * AT_P + (16 * et + 4 * tp) * 2); }
;             SCHED_BAR();
; #pragma unroll
;             for (int et = 0; et < 4; ++et) O[et] = __builtin_amdgcn_mfma_f32_16x16x32_bf16(cat8(tv[2 * et], tv[2 * et + 1]), Pf, O[et], 0, 0, 0);
;             SCHED_BAR(); }
;     ...
;         const float inv = 1.0f / l, lsv = mx + __logf(l);
;         if (g < 2) {
	v_add_f32_e32 v110, v24, v25
	v_cvt_pk_bf16_f32 v24, v146, v147
	v_mad_u64_u32 v[134:135], s[96:97], v132, s78, v[46:47]
	v_mad_u64_u32 v[146:147], s[96:97], v133, s78, v[46:47]
	ds_bpermute_b32 v111, v145, v110
	v_cvt_pk_bf16_f32 v25, v148, v149
	v_cvt_pk_bf16_f32 v26, v150, v151
	v_cvt_pk_bf16_f32 v27, v152, v153
	ds_read_b64_tr_b16 v[132:133], v134 offset:39168
	ds_read_b64_tr_b16 v[136:137], v134 offset:39200
	ds_read_b64_tr_b16 v[140:141], v134 offset:39232
	ds_read_b64_tr_b16 v[144:145], v134 offset:39264
	ds_read_b64_tr_b16 v[134:135], v146 offset:39168
	ds_read_b64_tr_b16 v[138:139], v146 offset:39200
	ds_read_b64_tr_b16 v[142:143], v146 offset:39232
	ds_read_b64_tr_b16 v[146:147], v146 offset:39264
	s_waitcnt lgkmcnt(3)
	v_mfma_f32_16x16x32_bf16 v[132:135], v[132:135], v[24:27], 0
	s_waitcnt lgkmcnt(2)
	v_mfma_f32_16x16x32_bf16 v[136:139], v[136:139], v[24:27], 0
	s_waitcnt lgkmcnt(1)
	v_mfma_f32_16x16x32_bf16 v[140:143], v[140:143], v[24:27], 0
	s_waitcnt lgkmcnt(0)
	v_mfma_f32_16x16x32_bf16 v[24:27], v[144:147], v[24:27], 0
	s_add_i32 s94, s92, s81
	s_add_i32 vcc_lo, s95, s81
	s_and_b64 s[96:97], s[48:49], exec
	s_cselect_b32 vcc_lo, vcc_lo, 0x100
	s_and_b64 s[96:97], s[46:47], exec
	v_cvt_pk_bf16_f32 v144, v122, v124
	s_cselect_b32 s94, s94, vcc_lo
	v_or_b32_e32 v122, s93, v43
	v_cvt_pk_bf16_f32 v145, v126, v127
	v_cvt_pk_bf16_f32 v146, v128, v129
	v_or_b32_e32 v124, s94, v43
	v_mad_u64_u32 v[128:129], s[96:97], v122, s78, v[46:47]
	v_cvt_pk_bf16_f32 v147, v130, v131
	v_mad_u64_u32 v[130:131], s[96:97], v124, s78, v[46:47]
	ds_read_b64_tr_b16 v[126:127], v128 offset:39168
	ds_read_b64_tr_b16 v[148:149], v128 offset:39200
	ds_read_b64_tr_b16 v[152:153], v128 offset:39232
	ds_read_b64_tr_b16 v[164:165], v128 offset:39264
	ds_read_b64_tr_b16 v[128:129], v130 offset:39168
	ds_read_b64_tr_b16 v[150:151], v130 offset:39200
	ds_read_b64_tr_b16 v[154:155], v130 offset:39232
	ds_read_b64_tr_b16 v[166:167], v130 offset:39264
	s_waitcnt lgkmcnt(0)
	v_mfma_f32_16x16x32_bf16 v[24:27], v[164:167], v[144:147], v[24:27]
	v_mfma_f32_16x16x32_bf16 v[126:129], v[126:129], v[144:147], v[132:135]
	v_mfma_f32_16x16x32_bf16 v[130:133], v[148:151], v[144:147], v[136:139]
	v_mfma_f32_16x16x32_bf16 v[134:137], v[152:155], v[144:147], v[140:143]
	s_add_i32 s93, s92, s83
	s_add_i32 s94, s95, s83
	s_and_b64 s[96:97], s[56:57], exec
	s_cselect_b32 s94, s94, 0x100
	s_and_b64 s[96:97], s[54:55], exec
	s_cselect_b32 s93, s93, s94
	v_cvt_pk_bf16_f32 v138, v114, v116
	v_or_b32_e32 v114, s2, v43
	v_or_b32_e32 v116, s93, v43
	v_cvt_pk_bf16_f32 v139, v118, v119
	v_cvt_pk_bf16_f32 v140, v120, v121
	v_mad_u64_u32 v[120:121], s[96:97], v114, s78, v[46:47]
	v_mad_u64_u32 v[148:149], s[96:97], v116, s78, v[46:47]
	v_cvt_pk_bf16_f32 v141, v123, v125
	ds_read_b64_tr_b16 v[118:119], v120 offset:39168
	ds_read_b64_tr_b16 v[122:123], v120 offset:39200
	ds_read_b64_tr_b16 v[142:143], v120 offset:39232
	ds_read_b64_tr_b16 v[146:147], v120 offset:39264
	ds_read_b64_tr_b16 v[120:121], v148 offset:39168
	ds_read_b64_tr_b16 v[124:125], v148 offset:39200
	ds_read_b64_tr_b16 v[144:145], v148 offset:39232
	ds_read_b64_tr_b16 v[148:149], v148 offset:39264
	s_waitcnt lgkmcnt(0)
	v_mfma_f32_16x16x32_bf16 v[24:27], v[146:149], v[138:141], v[24:27]
	v_mfma_f32_16x16x32_bf16 v[118:121], v[118:121], v[138:141], v[126:129]
	v_mfma_f32_16x16x32_bf16 v[122:125], v[122:125], v[138:141], v[130:133]
	v_mfma_f32_16x16x32_bf16 v[126:129], v[142:145], v[138:141], v[134:137]
	s_or_b32 s2, s92, 0x60
	s_add_i32 s94, s95, s85
	s_and_b64 s[92:93], s[64:65], exec
	s_cselect_b32 s94, s94, 0x100
	s_and_b64 s[92:93], s[62:63], exec
	v_cvt_pk_bf16_f32 v130, v34, v36
	s_cselect_b32 s2, s2, s94
	v_or_b32_e32 v34, s1, v43
	v_cvt_pk_bf16_f32 v131, v38, v39
	v_or_b32_e32 v36, s2, v43
	v_mad_u64_u32 v[38:39], s[92:93], v34, s78, v[46:47]
	v_cvt_pk_bf16_f32 v132, v112, v113
	v_cvt_pk_bf16_f32 v133, v115, v117
	v_mad_u64_u32 v[116:117], s[92:93], v36, s78, v[46:47]
	ds_read_b64_tr_b16 v[112:113], v38 offset:39168
	ds_read_b64_tr_b16 v[134:135], v38 offset:39200
	ds_read_b64_tr_b16 v[138:139], v38 offset:39232
	ds_read_b64_tr_b16 v[142:143], v38 offset:39264
	ds_read_b64_tr_b16 v[114:115], v116 offset:39168
	ds_read_b64_tr_b16 v[136:137], v116 offset:39200
	ds_read_b64_tr_b16 v[140:141], v116 offset:39232
	ds_read_b64_tr_b16 v[144:145], v116 offset:39264
	s_waitcnt lgkmcnt(0)
	v_mfma_f32_16x16x32_bf16 v[24:27], v[142:145], v[130:133], v[24:27]
	v_mfma_f32_16x16x32_bf16 v[112:115], v[112:115], v[130:133], v[118:121]
	v_mfma_f32_16x16x32_bf16 v[116:119], v[134:137], v[130:133], v[122:125]
	v_mfma_f32_16x16x32_bf16 v[120:123], v[138:141], v[130:133], v[126:129]
	s_add_i32 s95, s95, s87
	s_and_b64 s[92:93], s[38:39], exec
	v_cvt_pk_bf16_f32 v124, v28, v29
	s_cselect_b32 s1, s95, 0x100
	v_or_b32_e32 v28, s0, v43
	v_cvt_pk_bf16_f32 v125, v30, v31
	v_or_b32_e32 v29, s1, v43
	v_mad_u64_u32 v[30:31], s[0:1], v28, s78, v[46:47]
	v_cvt_pk_bf16_f32 v126, v32, v33
	v_cvt_pk_bf16_f32 v127, v35, v37
	v_mad_u64_u32 v[36:37], s[0:1], v29, s78, v[46:47]
	ds_read_b64_tr_b16 v[28:29], v30 offset:39168
	ds_read_b64_tr_b16 v[32:33], v30 offset:39200
	ds_read_b64_tr_b16 v[128:129], v30 offset:39232
	ds_read_b64_tr_b16 v[132:133], v30 offset:39264
	ds_read_b64_tr_b16 v[30:31], v36 offset:39168
	ds_read_b64_tr_b16 v[34:35], v36 offset:39200
	ds_read_b64_tr_b16 v[130:131], v36 offset:39232
	ds_read_b64_tr_b16 v[134:135], v36 offset:39264
	s_waitcnt lgkmcnt(3)
	v_mfma_f32_16x16x32_bf16 v[36:39], v[28:31], v[124:127], v[112:115]
	s_waitcnt lgkmcnt(2)
	v_mfma_f32_16x16x32_bf16 v[32:35], v[32:35], v[124:127], v[116:119]
	s_waitcnt lgkmcnt(1)
	v_mfma_f32_16x16x32_bf16 v[28:31], v[128:131], v[124:127], v[120:123]
	s_waitcnt lgkmcnt(0)
	v_mfma_f32_16x16x32_bf16 v[24:27], v[132:135], v[124:127], v[24:27]
	v_add_f32_e32 v110, v110, v111
	v_div_scale_f32 v111, s[0:1], v110, v110, 1.0
	v_rcp_f32_e32 v112, v111
	v_div_scale_f32 v113, vcc, 1.0, v110, 1.0
	s_mov_b32 s0, 0x800000
	v_fma_f32 v114, -v111, v112, 1.0
	v_fmac_f32_e32 v112, v114, v112
	v_mul_f32_e32 v114, v113, v112
	v_fma_f32 v115, -v111, v114, v113
	v_fmac_f32_e32 v114, v115, v112
	v_cmp_gt_f32_e64 s[0:1], s0, v110
	v_fma_f32 v111, -v111, v114, v113
	v_div_fmas_f32 v111, v111, v112, v114
	v_cndmask_b32_e64 v113, 0, 32, s[0:1]
	v_ldexp_f32 v113, v110, v113
	v_log_f32_e32 v113, v113
	v_div_fixup_f32 v110, v111, v110, 1.0
	s_mov_b32 s2, 0x3f317217
	v_cndmask_b32_e64 v112, 0, v83, s[0:1]
	v_mul_f32_e32 v111, 0x3f317217, v113
	v_fma_f32 v111, v113, s2, -v111
	v_fmac_f32_e32 v111, 0x3377d1cf, v113
	s_mov_b32 s2, 0x7f800000
	v_fmac_f32_e32 v111, 0x3f317217, v113
	v_cmp_lt_f32_e64 vcc, |v113|, s2
	s_mov_b64 s[0:1], -1
	s_nop 0
	v_cndmask_b32_e32 v111, v113, v111, vcc
	v_sub_f32_e32 v111, v111, v112
	v_add_f32_e32 v109, v109, v111
	s_and_b64 vcc, exec, s[76:77]
	s_cbranch_vccz .LBB0_1331
; __device__ __forceinline__ unsigned cvt_pk_bf16(float lo, float hi) { unsigned r; asm volatile("v_cvt_pk_bf16_f32 %0, %1, %2" : "=v"(r) : "v"(lo), "v"(hi)); return r; }
; __device__ __forceinline__ float bflo(unsigned w) { return __uint_as_float(w << 16); }
; __device__ __forceinline__ float bfhi(unsigned w) { return __uint_as_float(w & 0xffff0000u); }
; __device__ __forceinline__ void attn_unit(LAS unsigned char* lds, bf16_t* proj, bf16_t* og, float* lse, int unit) {
;     ...
;         } else {
;             const float mm = fmaxf(lsv, fmaxf(l0, l1)); float w0 = __expf(l0 - mm), w1 = __expf(l1 - mm), w2 = __expf(lsv - mm); const float iv = 1.0f / (w0 + w1 + w2);
;             w0 *= iv; w1 *= iv; w2 *= iv * inv;
;             bf16_t* dst = proj + rowq * DIN + QA_OFF + h * 64 + 4 * fq;
; #pragma unroll
;             for (int et = 0; et < 4; ++et) { const u32x2 a0 = c0[et], a1 = c1[et];
;                 const float r0 = bflo(a0.x) * w0 + bflo(a1.x) * w1 + O[et][0] * w2, r1 = bfhi(a0.x) * w0 + bfhi(a1.x) * w1 + O[et][1] * w2;
;                 const float r2 = bflo(a0.y) * w0 + bflo(a1.y) * w1 + O[et][2] * w2, r3 = bfhi(a0.y) * w0 + bfhi(a1.y) * w1 + O[et][3] * w2;
;                 u32x2 wv; wv.x = cvt_pk_bf16(r0, r1); wv.y = cvt_pk_bf16(r2, r3); *(u32x2*)(dst + 16 * et) = wv; }
;         }
	s_waitcnt vmcnt(6)
	v_max3_f32 v111, v109, v108, v55
	v_sub_f32_e32 v108, v108, v111
	v_mul_f32_e32 v108, 0x3fb8aa3b, v108
	v_sub_f32_e32 v55, v55, v111
	v_exp_f32_e32 v112, v108
	v_mul_f32_e32 v55, 0x3fb8aa3b, v55
	v_sub_f32_e32 v108, v109, v111
	v_exp_f32_e32 v55, v55
	v_mul_f32_e32 v108, 0x3fb8aa3b, v108
	v_exp_f32_e32 v113, v108
	v_lshlrev_b32_e32 v116, 16, v76
	v_add_f32_e32 v108, v112, v55
	v_and_b32_e32 v118, 0xffff0000, v76
	v_add_f32_e32 v108, v113, v108
	v_div_scale_f32 v76, s[0:1], v108, v108, 1.0
	v_rcp_f32_e32 v117, v76
	v_lshlrev_b32_e32 v111, 16, v78
	v_and_b32_e32 v78, 0xffff0000, v78
	v_lshlrev_b32_e32 v120, 16, v77
	v_fma_f32 v119, -v76, v117, 1.0
	v_fmac_f32_e32 v117, v119, v117
	v_div_scale_f32 v119, vcc, 1.0, v108, 1.0
	v_mul_f32_e32 v121, v119, v117
	v_fma_f32 v122, -v76, v121, v119
	v_fmac_f32_e32 v121, v122, v117
	v_fma_f32 v76, -v76, v121, v119
	v_div_fmas_f32 v76, v76, v117, v121
	v_div_fixup_f32 v122, v76, v108, 1.0
	v_mul_f32_e32 v123, v110, v122
	v_pk_mul_f32 v[112:113], v[112:113], v[122:123]
	v_mov_b32_e32 v117, v36
	v_mul_f32_e32 v55, v55, v122
	v_pk_mul_f32 v[116:117], v[112:113], v[116:117]
	v_mov_b32_e32 v119, v37
	v_fma_f32 v76, v55, v111, v116
	v_add_f32_e32 v108, v76, v117
	v_pk_mul_f32 v[116:117], v[112:113], v[118:119]
	v_mov_b32_e32 v121, v38
	v_fma_f32 v76, v55, v78, v116
	v_lshlrev_b32_e32 v124, 16, v79
	v_add_f32_e32 v78, v76, v117
	v_pk_mul_f32 v[116:117], v[112:113], v[120:121]
	v_and_b32_e32 v79, 0xffff0000, v79
	v_fma_f32 v76, v55, v124, v116
	v_add_f32_e32 v111, v76, v117
	v_and_b32_e32 v76, 0xffff0000, v77
	v_mov_b32_e32 v77, v39
	v_pk_mul_f32 v[76:77], v[112:113], v[76:77]
	v_mad_u64_u32 v[114:115], s[0:1], v62, s33, v[56:57]
	v_fma_f32 v76, v55, v79, v76
	v_add_f32_e32 v77, v76, v77
	v_mad_i32_i24 v115, v63, s33, v115
	v_cvt_pk_bf16_f32 v76, v108, v78
	v_cvt_pk_bf16_f32 v77, v111, v77
	global_store_dwordx2 v[114:115], v[76:77], off
	v_lshlrev_b32_e32 v76, 16, v72
	v_mov_b32_e32 v77, v32
	v_lshlrev_b32_e32 v78, 16, v74
	v_pk_mul_f32 v[76:77], v[112:113], v[76:77]
	s_mov_b64 s[0:1], 0
	v_fma_f32 v76, v55, v78, v76
	v_add_f32_e32 v78, v76, v77
	v_and_b32_e32 v76, 0xffff0000, v72
	v_mov_b32_e32 v77, v33
	v_and_b32_e32 v72, 0xffff0000, v74
	v_pk_mul_f32 v[76:77], v[112:113], v[76:77]
	s_nop 0
	v_fma_f32 v72, v55, v72, v76
	v_add_f32_e32 v74, v72, v77
	v_lshlrev_b32_e32 v76, 16, v73
	v_mov_b32_e32 v77, v34
	v_lshlrev_b32_e32 v72, 16, v75
	v_pk_mul_f32 v[76:77], v[112:113], v[76:77]
	v_and_b32_e32 v75, 0xffff0000, v75
	v_fma_f32 v72, v55, v72, v76
	v_add_f32_e32 v76, v72, v77
	v_and_b32_e32 v72, 0xffff0000, v73
	v_mov_b32_e32 v73, v35
	v_pk_mul_f32 v[72:73], v[112:113], v[72:73]
	s_nop 0
	v_fma_f32 v72, v55, v75, v72
	v_add_f32_e32 v73, v72, v73
	v_cvt_pk_bf16_f32 v72, v78, v74
	v_cvt_pk_bf16_f32 v73, v76, v73
	global_store_dwordx2 v[114:115], v[72:73], off offset:32
	v_lshlrev_b32_e32 v72, 16, v68
	v_mov_b32_e32 v73, v28
	v_lshlrev_b32_e32 v74, 16, v70
	v_pk_mul_f32 v[72:73], v[112:113], v[72:73]
	s_nop 0
	v_fma_f32 v72, v55, v74, v72
	v_add_f32_e32 v74, v72, v73
	v_and_b32_e32 v72, 0xffff0000, v68
	v_mov_b32_e32 v73, v29
	v_and_b32_e32 v68, 0xffff0000, v70
	v_pk_mul_f32 v[72:73], v[112:113], v[72:73]
	s_nop 0
	v_fma_f32 v68, v55, v68, v72
	v_add_f32_e32 v70, v68, v73
	v_lshlrev_b32_e32 v72, 16, v69
	v_mov_b32_e32 v73, v30
	v_lshlrev_b32_e32 v68, 16, v71
	v_pk_mul_f32 v[72:73], v[112:113], v[72:73]
	v_and_b32_e32 v71, 0xffff0000, v71
	v_fma_f32 v68, v55, v68, v72
	v_add_f32_e32 v72, v68, v73
	v_and_b32_e32 v68, 0xffff0000, v69
	v_mov_b32_e32 v69, v31
	v_pk_mul_f32 v[68:69], v[112:113], v[68:69]
	s_nop 0
	v_fma_f32 v68, v55, v71, v68
	v_add_f32_e32 v69, v68, v69
	v_cvt_pk_bf16_f32 v68, v74, v70
	v_cvt_pk_bf16_f32 v69, v72, v69
	global_store_dwordx2 v[114:115], v[68:69], off offset:64
	v_lshlrev_b32_e32 v68, 16, v64
	v_mov_b32_e32 v69, v24
	v_lshlrev_b32_e32 v70, 16, v66
	v_pk_mul_f32 v[68:69], v[112:113], v[68:69]
	s_nop 0
	v_fma_f32 v68, v55, v70, v68
	v_add_f32_e32 v70, v68, v69
	v_and_b32_e32 v68, 0xffff0000, v64
	v_mov_b32_e32 v69, v25
	v_and_b32_e32 v64, 0xffff0000, v66
	v_pk_mul_f32 v[68:69], v[112:113], v[68:69]
	s_nop 0
	v_fma_f32 v64, v55, v64, v68
	v_add_f32_e32 v66, v64, v69
	v_lshlrev_b32_e32 v68, 16, v65
	v_mov_b32_e32 v69, v26
	v_lshlrev_b32_e32 v64, 16, v67
	v_pk_mul_f32 v[68:69], v[112:113], v[68:69]
	v_and_b32_e32 v67, 0xffff0000, v67
	v_fma_f32 v64, v55, v64, v68
	v_add_f32_e32 v68, v64, v69
	v_and_b32_e32 v64, 0xffff0000, v65
	v_mov_b32_e32 v65, v27
	v_pk_mul_f32 v[64:65], v[112:113], v[64:65]
	s_nop 0
	v_fma_f32 v55, v55, v67, v64
	v_add_f32_e32 v55, v55, v65
	v_cvt_pk_bf16_f32 v64, v70, v66
	v_cvt_pk_bf16_f32 v65, v68, v55
	global_store_dwordx2 v[114:115], v[64:65], off offset:96
